# speedup vs baseline: 1.0139x; 1.0046x over previous
; #define SBAR() __builtin_amdgcn_sched_barrier(0)
; #define SLOAD(i, t) do { const long rb_ = TROW(t); const char* vt_ = (const char*)Vh + rb_ * (LDK * 2); const char* kt_ = (const char*)Kh + rb_ * (LDK * 2); \
;     sr_[i].vs0 = *(const bf16x8*)(vt_ + lo0); sr_[i].vs1 = *(const bf16x8*)(vt_ + lo0 + 32 * LDK * 2); \
;     sr_[i].ks0 = *(const bf16x8*)(kt_ + lo0); sr_[i].ks1 = *(const bf16x8*)(kt_ + lo0 + 32 * LDK * 2); } while (0)
; __device__ __forceinline__ void finishSM(f32x16& p0, f32x16& p1, float alpha, float& l_reg, bf16x8& pa0, bf16x8& pa1, bf16x8& pa2, bf16x8& pa3) {
; #pragma unroll
;   for (int r = 0; r < 16; ++r) p1[r] = __builtin_amdgcn_exp2f(p1[r]);
;   float ps = 0;
; #pragma unroll
;   for (int r = 0; r < 16; ++r) ps += p0[r];
; #pragma unroll
;   for (int r = 0; r < 16; ++r) ps += p1[r];
;   { auto rr = __builtin_amdgcn_permlane32_swap(__float_as_uint(ps), __float_as_uint(ps), false, false);
;     ps = __uint_as_float(rr[0]) + __uint_as_float(rr[1]); }
;   l_reg = l_reg * alpha + ps;
;     ...
;   PK4(p0, 0, pa0); PK4(p0, 8, pa1); PK4(p1, 0, pa2); PK4(p1, 8, pa3);
;     ...
; }
; __device__ __forceinline__ void qkt(f32x16& p0, f32x16& p1, const bf16_t* Ks, const bf16x8* qr, int r32, int hi) {
;   p0 = f32x16{}; p1 = f32x16{};
; #pragma unroll
;   for (int d0 = 0; d0 < 8; ++d0) { int cb = (d0 * 16 + hi * 8) * 2;
;     bf16x8 b0 = *reinterpret_cast<const bf16x8*>((const char*)Ks + KSWZ(r32, cb));
;     bf16x8 b1 = *reinterpret_cast<const bf16x8*>((const char*)Ks + KSWZ(32 + r32, cb));
;     p0 = __builtin_amdgcn_mfma_f32_32x32x16_bf16(b0, qr[d0], p0, 0, 0, 0);
;     p1 = __builtin_amdgcn_mfma_f32_32x32x16_bf16(b1, qr[d0], p1, 0, 0, 0); }
; }
; template <bool META>
; __device__ __forceinline__ void attn_unit(const bf16_t* Q, bf16_t* Oo, const bf16_t* __restrict__ Kb, const bf16_t* __restrict__ Vb, int b, int kvh, int h, int qb, char* lds, const int tid, const float* qn, const float* RT) {
;     ...
;     SBAR(); qkt(pB0, pB1, (bf16_t*)((char*)K_lds + bc * SHM_K), qr, r32, hi);
;     finishSM(pA0, pA1, alA, l_reg, pa0, pa1, pa2, pa3); SBAR();
;     SLOAD(SO, j + 1);
;     SBAR();
;     pv_d0(o, vb0 + bp * (int)SHM_V, pa0, pa1, pa2, pa3); partialSM(pB0, pB1, m_reg, mnB, alB);
.LBB0_260:
	s_mov_b32 s6, s28
	v_sub_co_u32_e64 v66, s[0:1], s6, 1
	s_and_b64 s[0:1], s[0:1], exec
	v_readfirstlane_b32 s0, v66
	s_cselect_b32 s28, 2, s0
	s_lshl_b32 s9, s6, 14
	s_add_i32 s0, s9, 0
	v_add_u32_e32 v70, s0, v182
	ds_read_b128 v[66:69], v70 offset:49152
	ds_read_b128 v[70:73], v70 offset:57344
	v_add_u32_e32 v193, s0, v183
	ds_read_b128 v[210:213], v193 offset:49152
	ds_read_b128 v[214:217], v193 offset:57344
	v_add_u32_e32 v193, s0, v184
	s_waitcnt lgkmcnt(3)
	v_mfma_f32_32x32x16_bf16 v[82:97], v[66:69], v[98:101], 0
	v_exp_f32_e32 v144, v144
	v_exp_f32_e32 v145, v145
	v_exp_f32_e32 v142, v142
	v_exp_f32_e32 v143, v143
	v_exp_f32_e32 v140, v140
	v_exp_f32_e32 v141, v141
	v_exp_f32_e32 v138, v138
	s_waitcnt lgkmcnt(2)
	v_mfma_f32_32x32x16_bf16 v[66:81], v[70:73], v[98:101], 0
	v_exp_f32_e32 v139, v139
	v_exp_f32_e32 v136, v136
	v_exp_f32_e32 v137, v137
	v_exp_f32_e32 v134, v134
	v_exp_f32_e32 v135, v135
	v_exp_f32_e32 v132, v132
	v_exp_f32_e32 v133, v133
	s_waitcnt lgkmcnt(1)
	v_mfma_f32_32x32x16_bf16 v[82:97], v[210:213], v[102:105], v[82:97]
	v_exp_f32_e32 v130, v130
	v_exp_f32_e32 v131, v131
	s_waitcnt lgkmcnt(0)
	v_mfma_f32_32x32x16_bf16 v[66:81], v[214:217], v[102:105], v[66:81]
	ds_read_b128 v[210:213], v193 offset:49152
	ds_read_b128 v[214:217], v193 offset:57344
	v_add_u32_e32 v193, s0, v185
	s_waitcnt lgkmcnt(1)
	v_mfma_f32_32x32x16_bf16 v[82:97], v[210:213], v[106:109], v[82:97]
	s_waitcnt lgkmcnt(0)
	v_mfma_f32_32x32x16_bf16 v[66:81], v[214:217], v[106:109], v[66:81]
	ds_read_b128 v[210:213], v193 offset:49152
	ds_read_b128 v[214:217], v193 offset:57344
	v_add_u32_e32 v193, s0, v186
	s_waitcnt lgkmcnt(1)
	v_mfma_f32_32x32x16_bf16 v[82:97], v[210:213], v[110:113], v[82:97]
	s_waitcnt lgkmcnt(0)
	v_mfma_f32_32x32x16_bf16 v[66:81], v[214:217], v[110:113], v[66:81]
	ds_read_b128 v[210:213], v193 offset:49152
	ds_read_b128 v[214:217], v193 offset:57344
	v_add_u32_e32 v193, s0, v187
	s_waitcnt lgkmcnt(1)
	v_mfma_f32_32x32x16_bf16 v[82:97], v[210:213], v[114:117], v[82:97]
	s_waitcnt lgkmcnt(0)
	v_mfma_f32_32x32x16_bf16 v[66:81], v[214:217], v[114:117], v[66:81]
	ds_read_b128 v[210:213], v193 offset:49152
	ds_read_b128 v[214:217], v193 offset:57344
	v_add_u32_e32 v193, s0, v188
	s_waitcnt lgkmcnt(1)
	v_mfma_f32_32x32x16_bf16 v[82:97], v[210:213], v[118:121], v[82:97]
	s_waitcnt lgkmcnt(0)
	v_mfma_f32_32x32x16_bf16 v[66:81], v[214:217], v[118:121], v[66:81]
	ds_read_b128 v[210:213], v193 offset:49152
	ds_read_b128 v[214:217], v193 offset:57344
	v_add_u32_e32 v193, s0, v189
	s_waitcnt lgkmcnt(1)
	v_mfma_f32_32x32x16_bf16 v[82:97], v[210:213], v[122:125], v[82:97]
	s_waitcnt lgkmcnt(0)
	v_mfma_f32_32x32x16_bf16 v[66:81], v[214:217], v[122:125], v[66:81]
	ds_read_b128 v[210:213], v193 offset:49152
	ds_read_b128 v[214:217], v193 offset:57344
	v_add_f32_e32 v193, v147, v146
	v_add_f32_e32 v193, v148, v193
	v_add_f32_e32 v193, v159, v193
	v_add_f32_e32 v193, v160, v193
	v_add_f32_e32 v193, v209, v193
	v_add_f32_e32 v193, v149, v193
	v_add_f32_e32 v193, v161, v193
	v_add_f32_e32 v193, v151, v193
	v_add_f32_e32 v193, v153, v193
	v_add_f32_e32 v193, v154, v193
	v_add_f32_e32 v193, v157, v193
	v_add_f32_e32 v193, v152, v193
	v_add_f32_e32 v193, v155, v193
	v_add_f32_e32 v193, v156, v193
	v_add_f32_e32 v193, v158, v193
	v_add_f32_e32 v193, v144, v193
	v_add_f32_e32 v193, v145, v193
	v_add_f32_e32 v193, v142, v193
	v_add_f32_e32 v193, v143, v193
	v_add_f32_e32 v193, v140, v193
	v_add_f32_e32 v193, v141, v193
	v_add_f32_e32 v193, v138, v193
	v_add_f32_e32 v193, v139, v193
	v_add_f32_e32 v193, v136, v193
	v_add_f32_e32 v193, v137, v193
	s_waitcnt lgkmcnt(1)
	v_mfma_f32_32x32x16_bf16 v[82:97], v[210:213], v[126:129], v[82:97]
	v_add_f32_e32 v193, v134, v193
	v_add_f32_e32 v193, v135, v193
	v_add_f32_e32 v193, v132, v193
	v_add_f32_e32 v193, v133, v193
	v_add_f32_e32 v193, v130, v193
	v_add_f32_e32 v193, v131, v193
	v_mov_b32_e32 v195, v193
	s_waitcnt lgkmcnt(0)
	v_mfma_f32_32x32x16_bf16 v[66:81], v[214:217], v[126:129], v[66:81]
	v_cvt_pk_bf16_f32 v146, v146, v147
	v_cvt_pk_bf16_f32 v147, v148, v159
	v_cvt_pk_bf16_f32 v148, v160, v209
	v_permlane32_swap_b32_e32 v193, v195
	v_cvt_pk_bf16_f32 v149, v149, v161
	v_permlane32_swap_b32_e32 v146, v148
	v_cvt_pk_bf16_f32 v210, v151, v153
	v_cvt_pk_bf16_f32 v211, v154, v157
	v_cvt_pk_bf16_f32 v212, v152, v155
	v_cvt_pk_bf16_f32 v213, v156, v158
	v_cvt_pk_bf16_f32 v152, v144, v145
	v_cvt_pk_bf16_f32 v153, v142, v143
	v_cvt_pk_bf16_f32 v154, v140, v141
	v_cvt_pk_bf16_f32 v155, v138, v139
	v_cvt_pk_bf16_f32 v156, v136, v137
	v_cvt_pk_bf16_f32 v157, v134, v135
	v_cvt_pk_bf16_f32 v158, v132, v133
	v_cvt_pk_bf16_f32 v159, v130, v131
	v_permlane32_swap_b32_e32 v147, v149
	v_permlane32_swap_b32_e32 v210, v212
	v_permlane32_swap_b32_e32 v211, v213
	v_permlane32_swap_b32_e32 v152, v154
	v_permlane32_swap_b32_e32 v153, v155
	v_permlane32_swap_b32_e32 v156, v158
	v_permlane32_swap_b32_e32 v157, v159
	s_cmpk_lg_i32 s4, 0xfd
	s_cselect_b64 s[0:1], -1, 0
	s_cmpk_eq_i32 s4, 0xfd
	s_cselect_b64 s[40:41], -1, 0
	s_and_b64 s[10:11], s[40:41], exec
	s_cselect_b32 s11, s44, s91
	s_cselect_b32 s10, s31, s90
	s_lshl_b64 s[10:11], s[10:11], 9
	v_lshl_add_u64 v[130:131], v[168:169], 0, s[10:11]
	v_add_co_u32_e32 v134, vcc, s37, v130
	v_lshl_add_u64 v[138:139], v[170:171], 0, s[10:11]
	s_nop 0
	v_addc_co_u32_e32 v135, vcc, 0, v131, vcc
	v_add_co_u32_e32 v142, vcc, s37, v138
	global_load_dwordx4 v[130:133], v[130:131], off
	global_load_dwordx4 v[134:137], v[134:135], off
	v_addc_co_u32_e32 v143, vcc, 0, v139, vcc
	global_load_dwordx4 v[138:141], v[138:139], off
	global_load_dwordx4 v[142:145], v[142:143], off
	s_lshl_b32 s8, s28, 14
	v_add_u32_e32 v151, s8, v178
	ds_read_b64_tr_b16 v[214:215], v151 offset:0
	ds_read_b64_tr_b16 v[216:217], v151 offset:0x800
	ds_read_b64_tr_b16 v[218:219], v151 offset:0x1000
	ds_read_b64_tr_b16 v[220:221], v151 offset:0x1800
	ds_read_b64_tr_b16 v[222:223], v151 offset:0x2000
	ds_read_b64_tr_b16 v[224:225], v151 offset:0x2800
	ds_read_b64_tr_b16 v[226:227], v151 offset:0x3000
	ds_read_b64_tr_b16 v[228:229], v151 offset:0x3800
	s_waitcnt lgkmcnt(6)
; #define SBAR() __builtin_amdgcn_sched_barrier(0)
; __device__ __forceinline__ void partialSM(f32x16& p0, f32x16& p1, float& m_reg, float& mn, float& alpha) {
;   constexpr float C = ASCALE * 1.4426950408889634f;
;   float pmax = p0[0];
; #pragma unroll
;   for (int r = 1; r < 16; ++r) pmax = fmaxf(pmax, p0[r]);
; #pragma unroll
;   for (int r = 0; r < 16; ++r) pmax = fmaxf(pmax, p1[r]);
;   { auto rr = __builtin_amdgcn_permlane32_swap(__float_as_uint(pmax), __float_as_uint(pmax), false, false);
;     pmax = fmaxf(__uint_as_float(rr[0]), __uint_as_float(rr[1])); }
;   if (__builtin_expect(__all(pmax - m_reg <= ATHR / ASCALE), 1)) { mn = m_reg; alpha = 1.f; }
;   else { mn = fmaxf(m_reg, pmax); alpha = __builtin_amdgcn_exp2f((m_reg - mn) * C); m_reg = mn; }
; template <int D0> __device__ __forceinline__ void pv_one(f32x16& od, int vb, bf16x8 pa0, bf16x8 pa1, bf16x8 pa2, bf16x8 pa3) {
;   const s16x4 l0 = tr_read<v_rd_off(D0, 0, 0)>(vb), h0 = tr_read<v_rd_off(D0, 0, 1)>(vb), l1 = tr_read<v_rd_off(D0, 1, 0)>(vb), h1 = tr_read<v_rd_off(D0, 1, 1)>(vb);
;   const s16x4 l2 = tr_read<v_rd_off(D0, 2, 0)>(vb), h2 = tr_read<v_rd_off(D0, 2, 1)>(vb), l3 = tr_read<v_rd_off(D0, 3, 0)>(vb), h3 = tr_read<v_rd_off(D0, 3, 1)>(vb);
;   asm volatile("s_waitcnt lgkmcnt(0)" ::: "memory"); SBAR();
;     ...
;   od = __builtin_amdgcn_mfma_f32_32x32x16_bf16(pa0, PK(l0, h0), od, 0, 0, 0);
;   od = __builtin_amdgcn_mfma_f32_32x32x16_bf16(pa1, PK(l1, h1), od, 0, 0, 0);
;   od = __builtin_amdgcn_mfma_f32_32x32x16_bf16(pa2, PK(l2, h2), od, 0, 0, 0);
;   od = __builtin_amdgcn_mfma_f32_32x32x16_bf16(pa3, PK(l3, h3), od, 0, 0, 0);
;     ...
; }
; __device__ __forceinline__ void pv_d0(f32x16* o, int vb, bf16x8 pa0, bf16x8 pa1, bf16x8 pa2, bf16x8 pa3) {
;   pv_one<0>(o[0], vb, pa0, pa1, pa2, pa3); pv_one<1>(o[1], vb, pa0, pa1, pa2, pa3); pv_one<2>(o[2], vb, pa0, pa1, pa2, pa3); pv_one<3>(o[3], vb, pa0, pa1, pa2, pa3);
; }
	s_nop 0
	v_mfma_f32_32x32x16_bf16 v[2:17], v[146:149], v[214:217], v[2:17]
	ds_read_b64_tr_b16 v[214:215], v151 offset:0x200
	ds_read_b64_tr_b16 v[216:217], v151 offset:0xa00
	s_waitcnt lgkmcnt(6)
	v_mfma_f32_32x32x16_bf16 v[2:17], v[210:213], v[218:221], v[2:17]
	ds_read_b64_tr_b16 v[218:219], v151 offset:0x1200
	ds_read_b64_tr_b16 v[220:221], v151 offset:0x1a00
	s_waitcnt lgkmcnt(6)
	v_mfma_f32_32x32x16_bf16 v[2:17], v[152:155], v[222:225], v[2:17]
	ds_read_b64_tr_b16 v[222:223], v151 offset:0x2200
	ds_read_b64_tr_b16 v[224:225], v151 offset:0x2a00
	s_waitcnt lgkmcnt(6)
	v_mfma_f32_32x32x16_bf16 v[2:17], v[156:159], v[226:229], v[2:17]
	ds_read_b64_tr_b16 v[226:227], v151 offset:0x3200
	ds_read_b64_tr_b16 v[228:229], v151 offset:0x3a00
	s_waitcnt lgkmcnt(6)
	v_mfma_f32_32x32x16_bf16 v[50:65], v[146:149], v[214:217], v[50:65]
	ds_read_b64_tr_b16 v[214:215], v151 offset:0x400
	ds_read_b64_tr_b16 v[216:217], v151 offset:0xc00
	s_waitcnt lgkmcnt(6)
	v_mfma_f32_32x32x16_bf16 v[50:65], v[210:213], v[218:221], v[50:65]
	ds_read_b64_tr_b16 v[218:219], v151 offset:0x1400
	ds_read_b64_tr_b16 v[220:221], v151 offset:0x1c00
	s_waitcnt lgkmcnt(6)
	v_mfma_f32_32x32x16_bf16 v[50:65], v[152:155], v[222:225], v[50:65]
	ds_read_b64_tr_b16 v[222:223], v151 offset:0x2400
	ds_read_b64_tr_b16 v[224:225], v151 offset:0x2c00
	s_waitcnt lgkmcnt(6)
	v_mfma_f32_32x32x16_bf16 v[50:65], v[156:159], v[226:229], v[50:65]
	ds_read_b64_tr_b16 v[226:227], v151 offset:0x3400
	ds_read_b64_tr_b16 v[228:229], v151 offset:0x3c00
	s_waitcnt lgkmcnt(6)
	v_mfma_f32_32x32x16_bf16 v[34:49], v[146:149], v[214:217], v[34:49]
	ds_read_b64_tr_b16 v[214:215], v151 offset:0x600
	ds_read_b64_tr_b16 v[216:217], v151 offset:0xe00
	s_waitcnt lgkmcnt(6)
	v_mfma_f32_32x32x16_bf16 v[34:49], v[210:213], v[218:221], v[34:49]
	ds_read_b64_tr_b16 v[218:219], v151 offset:0x1600
	ds_read_b64_tr_b16 v[220:221], v151 offset:0x1e00
	s_waitcnt lgkmcnt(6)
	v_mfma_f32_32x32x16_bf16 v[34:49], v[152:155], v[222:225], v[34:49]
	ds_read_b64_tr_b16 v[222:223], v151 offset:0x2600
	ds_read_b64_tr_b16 v[224:225], v151 offset:0x2e00
	s_waitcnt lgkmcnt(6)
	v_mfma_f32_32x32x16_bf16 v[34:49], v[156:159], v[226:229], v[34:49]
	ds_read_b64_tr_b16 v[226:227], v151 offset:0x3600
	ds_read_b64_tr_b16 v[228:229], v151 offset:0x3e00
	s_waitcnt lgkmcnt(6)
	v_mfma_f32_32x32x16_bf16 v[18:33], v[146:149], v[214:217], v[18:33]
	v_max_f32_e32 v146, v82, v83
	v_max3_f32 v146, v146, v84, v85
	v_max3_f32 v146, v146, v86, v87
	v_max3_f32 v146, v146, v88, v89
	v_max3_f32 v146, v146, v90, v91
	v_max3_f32 v146, v146, v92, v93
	v_max3_f32 v146, v146, v94, v95
	v_max3_f32 v146, v146, v96, v97
	v_max3_f32 v146, v146, v66, v67
	s_waitcnt lgkmcnt(4)
	v_mfma_f32_32x32x16_bf16 v[18:33], v[210:213], v[218:221], v[18:33]
	v_max3_f32 v146, v146, v68, v69
	v_max3_f32 v146, v146, v70, v71
	v_max3_f32 v146, v146, v72, v73
	v_max3_f32 v146, v146, v74, v75
	v_max3_f32 v146, v146, v76, v77
	v_max3_f32 v146, v146, v78, v79
	v_max3_f32 v146, v146, v80, v81
	v_mov_b32_e32 v147, v146
	s_waitcnt lgkmcnt(2)
	v_mfma_f32_32x32x16_bf16 v[18:33], v[152:155], v[222:225], v[18:33]
	s_nop 0
	v_permlane32_swap_b32_e32 v146, v147
	v_max_f32_e32 v146, v146, v147
	v_sub_f32_e32 v147, v146, v150
	v_cmp_ge_f32_e32 vcc, s25, v147
	v_max_f32_e32 v146, v150, v146
	v_sub_f32_e32 v147, v150, v146
	s_cmp_eq_u64 vcc, exec
	v_mul_f32_e32 v147, 0x3e0293ee, v147
	s_waitcnt lgkmcnt(0)
	v_mfma_f32_32x32x16_bf16 v[18:33], v[156:159], v[226:229], v[18:33]
	s_cselect_b64 s[42:43], -1, 0
	v_exp_f32_e32 v147, v147
	s_add_i32 s7, s9, 0x4000
	s_cmp_lg_u32 s6, 2
	s_cselect_b32 s6, s7, 0
	s_add_i32 s10, s6, 0
	v_cndmask_b32_e64 v196, v147, 1.0, s[42:43]
	v_add_u32_e32 v147, s10, v176
	s_waitcnt vmcnt(0)
	s_waitcnt vmcnt(3)
	ds_write_b128 v147, v[130:133]
	s_waitcnt vmcnt(2)
	ds_write_b128 v147, v[134:137] offset:8192
	v_add_u32_e32 v147, s10, v179
	s_waitcnt vmcnt(1)
	ds_write_b128 v147, v[138:141] offset:49152
	v_cmp_gt_f32_e32 vcc, 1.0, v196
	s_waitcnt vmcnt(0)
	ds_write_b128 v147, v[142:145] offset:57344
	s_cbranch_vccz .LBB0_264
	s_and_saveexec_b64 s[6:7], s[38:39]
	ds_write_b32 v190, v196 offset:128
	s_or_b64 exec, exec, s[6:7]
	s_waitcnt lgkmcnt(0)
	v_add_u32_e32 v147, v173, v181
	ds_read_b128 v[152:155], v147 offset:224
	ds_read_b128 v[156:159], v147 offset:192
	ds_read_b128 v[210:213], v147 offset:160
	ds_read_b128 v[214:217], v147 offset:128
	s_waitcnt lgkmcnt(3)
	v_pk_mul_f32 v[14:15], v[14:15], v[152:153]
	s_waitcnt lgkmcnt(2)
	v_pk_mul_f32 v[10:11], v[10:11], v[156:157]
	s_waitcnt lgkmcnt(1)
	v_pk_mul_f32 v[6:7], v[6:7], v[210:211]
	v_pk_mul_f32 v[16:17], v[16:17], v[154:155]
	v_pk_mul_f32 v[12:13], v[12:13], v[158:159]
	v_pk_mul_f32 v[8:9], v[8:9], v[212:213]
	s_waitcnt lgkmcnt(0)
	v_pk_mul_f32 v[4:5], v[4:5], v[216:217]
	v_pk_mul_f32 v[2:3], v[2:3], v[214:215]
	v_pk_mul_f32 v[62:63], v[62:63], v[152:153]
	v_pk_mul_f32 v[58:59], v[58:59], v[156:157]
	v_pk_mul_f32 v[54:55], v[54:55], v[210:211]
	v_pk_mul_f32 v[64:65], v[64:65], v[154:155]
	v_pk_mul_f32 v[60:61], v[60:61], v[158:159]
	v_pk_mul_f32 v[56:57], v[56:57], v[212:213]
	v_pk_mul_f32 v[52:53], v[52:53], v[216:217]
	v_pk_mul_f32 v[50:51], v[50:51], v[214:215]
	v_pk_mul_f32 v[46:47], v[46:47], v[152:153]
	v_pk_mul_f32 v[42:43], v[42:43], v[156:157]
	v_pk_mul_f32 v[38:39], v[38:39], v[210:211]
	v_pk_mul_f32 v[48:49], v[48:49], v[154:155]
	v_pk_mul_f32 v[44:45], v[44:45], v[158:159]
	v_pk_mul_f32 v[40:41], v[40:41], v[212:213]
	v_pk_mul_f32 v[36:37], v[36:37], v[216:217]
	v_pk_mul_f32 v[34:35], v[34:35], v[214:215]
	v_pk_mul_f32 v[30:31], v[30:31], v[152:153]
	v_pk_mul_f32 v[26:27], v[26:27], v[156:157]
	v_pk_mul_f32 v[22:23], v[22:23], v[210:211]
	v_pk_mul_f32 v[32:33], v[32:33], v[154:155]
	v_pk_mul_f32 v[28:29], v[28:29], v[158:159]
	v_pk_mul_f32 v[24:25], v[24:25], v[212:213]
	v_pk_mul_f32 v[20:21], v[20:21], v[216:217]
	v_pk_mul_f32 v[18:19], v[18:19], v[214:215]
; __device__ __forceinline__ void partialSM(f32x16& p0, f32x16& p1, float& m_reg, float& mn, float& alpha) {
;     ...
;   float mnC = -mn * C;
; #pragma unroll
;   for (int r = 0; r < 16; ++r) p0[r] = fmaf(p0[r], C, mnC);
; #pragma unroll
;   for (int r = 0; r < 16; ++r) p1[r] = fmaf(p1[r], C, mnC);
; #pragma unroll
;   for (int r = 0; r < 16; ++r) p0[r] = __builtin_amdgcn_exp2f(p0[r]);
.LBB0_264:
	v_cndmask_b32_e64 v209, v146, v150, s[42:43]
	v_mul_f32_e32 v154, 0xbe0293ee, v209
	s_add_i32 s4, s4, 2
	v_fmamk_f32 v82, v82, 0x3e0293ee, v154
	v_fmamk_f32 v83, v83, 0x3e0293ee, v154
	v_fmamk_f32 v84, v84, 0x3e0293ee, v154
	v_fmamk_f32 v85, v85, 0x3e0293ee, v154
	v_fmamk_f32 v86, v86, 0x3e0293ee, v154
	v_fmamk_f32 v87, v87, 0x3e0293ee, v154
	v_fmamk_f32 v88, v88, 0x3e0293ee, v154
	v_fmamk_f32 v89, v89, 0x3e0293ee, v154
	v_fmamk_f32 v90, v90, 0x3e0293ee, v154
	v_fmamk_f32 v91, v91, 0x3e0293ee, v154
	v_fmamk_f32 v92, v92, 0x3e0293ee, v154
	v_fmamk_f32 v93, v93, 0x3e0293ee, v154
	v_fmamk_f32 v94, v94, 0x3e0293ee, v154
	v_fmamk_f32 v95, v95, 0x3e0293ee, v154
	v_fmamk_f32 v96, v96, 0x3e0293ee, v154
	v_fmamk_f32 v97, v97, 0x3e0293ee, v154
	v_fmamk_f32 v155, v66, 0x3e0293ee, v154
	v_fmamk_f32 v156, v67, 0x3e0293ee, v154
	v_fmamk_f32 v157, v68, 0x3e0293ee, v154
	v_fmamk_f32 v158, v69, 0x3e0293ee, v154
	v_fmamk_f32 v159, v70, 0x3e0293ee, v154
	v_fmamk_f32 v160, v71, 0x3e0293ee, v154
	v_fmamk_f32 v161, v72, 0x3e0293ee, v154
	v_fmamk_f32 v198, v73, 0x3e0293ee, v154
	v_fmamk_f32 v199, v74, 0x3e0293ee, v154
	v_fmamk_f32 v200, v75, 0x3e0293ee, v154
	v_fmamk_f32 v201, v76, 0x3e0293ee, v154
	v_fmamk_f32 v202, v77, 0x3e0293ee, v154
	v_fmamk_f32 v203, v78, 0x3e0293ee, v154
	v_fmamk_f32 v204, v79, 0x3e0293ee, v154
	v_fmamk_f32 v205, v80, 0x3e0293ee, v154
	v_fmac_f32_e32 v154, 0x3e0293ee, v81
	v_exp_f32_e32 v206, v82
	v_exp_f32_e32 v207, v83
	v_exp_f32_e32 v212, v84
	v_exp_f32_e32 v213, v85
	v_exp_f32_e32 v214, v86
	v_exp_f32_e32 v215, v87
	v_exp_f32_e32 v216, v88
	v_exp_f32_e32 v217, v89
	v_exp_f32_e32 v218, v90
	v_exp_f32_e32 v219, v91
	v_exp_f32_e32 v220, v92
	v_exp_f32_e32 v221, v93
	v_exp_f32_e32 v222, v94
	v_exp_f32_e32 v223, v95
	v_exp_f32_e32 v224, v96
	v_exp_f32_e32 v225, v97
	s_waitcnt lgkmcnt(0)
	s_barrier
; #define SBAR() __builtin_amdgcn_sched_barrier(0)
; #define SLOAD(i, t) do { const long rb_ = TROW(t); const char* vt_ = (const char*)Vh + rb_ * (LDK * 2); const char* kt_ = (const char*)Kh + rb_ * (LDK * 2); \
;     sr_[i].vs0 = *(const bf16x8*)(vt_ + lo0); sr_[i].vs1 = *(const bf16x8*)(vt_ + lo0 + 32 * LDK * 2); \
;     sr_[i].ks0 = *(const bf16x8*)(kt_ + lo0); sr_[i].ks1 = *(const bf16x8*)(kt_ + lo0 + 32 * LDK * 2); } while (0)
; __device__ __forceinline__ void finishSM(f32x16& p0, f32x16& p1, float alpha, float& l_reg, bf16x8& pa0, bf16x8& pa1, bf16x8& pa2, bf16x8& pa3) {
; #pragma unroll
;   for (int r = 0; r < 16; ++r) p1[r] = __builtin_amdgcn_exp2f(p1[r]);
;   float ps = 0;
; #pragma unroll
;   for (int r = 0; r < 16; ++r) ps += p0[r];
; #pragma unroll
;   for (int r = 0; r < 16; ++r) ps += p1[r];
;   { auto rr = __builtin_amdgcn_permlane32_swap(__float_as_uint(ps), __float_as_uint(ps), false, false);
;     ps = __uint_as_float(rr[0]) + __uint_as_float(rr[1]); }
;   l_reg = l_reg * alpha + ps;
;     ...
;   PK4(p0, 0, pa0); PK4(p0, 8, pa1); PK4(p1, 0, pa2); PK4(p1, 8, pa3);
;     ...
; }
; __device__ __forceinline__ void qkt(f32x16& p0, f32x16& p1, const bf16_t* Ks, const bf16x8* qr, int r32, int hi) {
;   p0 = f32x16{}; p1 = f32x16{};
; #pragma unroll
;   for (int d0 = 0; d0 < 8; ++d0) { int cb = (d0 * 16 + hi * 8) * 2;
;     bf16x8 b0 = *reinterpret_cast<const bf16x8*>((const char*)Ks + KSWZ(r32, cb));
;     bf16x8 b1 = *reinterpret_cast<const bf16x8*>((const char*)Ks + KSWZ(32 + r32, cb));
;     p0 = __builtin_amdgcn_mfma_f32_32x32x16_bf16(b0, qr[d0], p0, 0, 0, 0);
;     p1 = __builtin_amdgcn_mfma_f32_32x32x16_bf16(b1, qr[d0], p1, 0, 0, 0); }
; }
; template <bool META>
; __device__ __forceinline__ void attn_unit(const bf16_t* Q, bf16_t* Oo, const bf16_t* __restrict__ Kb, const bf16_t* __restrict__ Vb, int b, int kvh, int h, int qb, char* lds, const int tid, const float* qn, const float* RT) {
;     ...
;     SBAR(); qkt(pA0, pA1, (bf16_t*)((char*)K_lds + bn * SHM_K), qr, r32, hi);
;     if (j + 1 == NT - 1) mask_last(pA0, pA1);
;     finishSM(pB0, pB1, alB, l_reg, pa0, pa1, pa2, pa3); SBAR();
;     if (j + 2 < NT) SLOAD(SE, j + 2);
	v_add_u32_e32 v70, s10, v182
	ds_read_b128 v[66:69], v70 offset:49152
	ds_read_b128 v[82:85], v70 offset:57344
	v_add_u32_e32 v150, s10, v183
	ds_read_b128 v[146:149], v150 offset:49152
	ds_read_b128 v[150:153], v150 offset:57344
	v_exp_f32_e32 v155, v155
	s_waitcnt lgkmcnt(3)
	v_mfma_f32_32x32x16_bf16 v[66:81], v[66:69], v[98:101], 0
	v_exp_f32_e32 v156, v156
	v_exp_f32_e32 v157, v157
	v_exp_f32_e32 v158, v158
	v_exp_f32_e32 v159, v159
	v_exp_f32_e32 v160, v160
	v_exp_f32_e32 v161, v161
	v_exp_f32_e32 v198, v198
	s_waitcnt lgkmcnt(2)
	v_mfma_f32_32x32x16_bf16 v[82:97], v[82:85], v[98:101], 0
	v_exp_f32_e32 v199, v199
	v_exp_f32_e32 v200, v200
	v_exp_f32_e32 v201, v201
	v_exp_f32_e32 v202, v202
	v_exp_f32_e32 v203, v203
	v_exp_f32_e32 v204, v204
	v_exp_f32_e32 v205, v205
	s_waitcnt lgkmcnt(1)
	v_mfma_f32_32x32x16_bf16 v[66:81], v[146:149], v[102:105], v[66:81]
	v_exp_f32_e32 v226, v154
	v_cvt_pk_bf16_f32 v154, v155, v156
	s_waitcnt lgkmcnt(0)
	v_mfma_f32_32x32x16_bf16 v[82:97], v[150:153], v[102:105], v[82:97]
	v_add_u32_e32 v150, s10, v184
	ds_read_b128 v[146:149], v150 offset:49152
	ds_read_b128 v[150:153], v150 offset:57344
	s_waitcnt lgkmcnt(1)
	v_mfma_f32_32x32x16_bf16 v[66:81], v[146:149], v[106:109], v[66:81]
	s_waitcnt lgkmcnt(0)
	v_mfma_f32_32x32x16_bf16 v[82:97], v[150:153], v[106:109], v[82:97]
	v_add_u32_e32 v150, s10, v185
	ds_read_b128 v[146:149], v150 offset:49152
	ds_read_b128 v[150:153], v150 offset:57344
	s_waitcnt lgkmcnt(1)
	v_mfma_f32_32x32x16_bf16 v[66:81], v[146:149], v[110:113], v[66:81]
	s_waitcnt lgkmcnt(0)
	v_mfma_f32_32x32x16_bf16 v[82:97], v[150:153], v[110:113], v[82:97]
	v_add_u32_e32 v150, s10, v186
	ds_read_b128 v[146:149], v150 offset:49152
	ds_read_b128 v[150:153], v150 offset:57344
	s_waitcnt lgkmcnt(1)
	v_mfma_f32_32x32x16_bf16 v[66:81], v[146:149], v[114:117], v[66:81]
	s_waitcnt lgkmcnt(0)
	v_mfma_f32_32x32x16_bf16 v[82:97], v[150:153], v[114:117], v[82:97]
	v_add_u32_e32 v150, s10, v187
	ds_read_b128 v[146:149], v150 offset:49152
	ds_read_b128 v[150:153], v150 offset:57344
	s_waitcnt lgkmcnt(1)
	v_mfma_f32_32x32x16_bf16 v[66:81], v[146:149], v[118:121], v[66:81]
	s_waitcnt lgkmcnt(0)
	v_mfma_f32_32x32x16_bf16 v[82:97], v[150:153], v[118:121], v[82:97]
	v_add_u32_e32 v150, s10, v188
	ds_read_b128 v[146:149], v150 offset:49152
	ds_read_b128 v[150:153], v150 offset:57344
	s_waitcnt lgkmcnt(1)
	v_mfma_f32_32x32x16_bf16 v[66:81], v[146:149], v[122:125], v[66:81]
	s_waitcnt lgkmcnt(0)
	v_mfma_f32_32x32x16_bf16 v[82:97], v[150:153], v[122:125], v[82:97]
	v_add_u32_e32 v150, s10, v189
	ds_read_b128 v[146:149], v150 offset:49152
	ds_read_b128 v[150:153], v150 offset:57344
	s_waitcnt lgkmcnt(1)
	v_mfma_f32_32x32x16_bf16 v[66:81], v[146:149], v[126:129], v[66:81]
	v_add_f32_e32 v146, v207, v206
	v_add_f32_e32 v146, v212, v146
	v_add_f32_e32 v146, v213, v146
	v_add_f32_e32 v146, v214, v146
	v_add_f32_e32 v146, v215, v146
	v_add_f32_e32 v146, v216, v146
	v_add_f32_e32 v146, v217, v146
	v_add_f32_e32 v146, v218, v146
	v_add_f32_e32 v146, v219, v146
	v_add_f32_e32 v146, v220, v146
	v_add_f32_e32 v146, v221, v146
	v_add_f32_e32 v146, v222, v146
	v_add_f32_e32 v146, v223, v146
	v_add_f32_e32 v146, v224, v146
	v_add_f32_e32 v146, v225, v146
	v_add_f32_e32 v146, v155, v146
	v_add_f32_e32 v146, v156, v146
	v_add_f32_e32 v146, v157, v146
	v_add_f32_e32 v146, v158, v146
	v_add_f32_e32 v146, v159, v146
	v_add_f32_e32 v146, v160, v146
	v_add_f32_e32 v146, v161, v146
	v_add_f32_e32 v146, v198, v146
	v_add_f32_e32 v146, v199, v146
	v_add_f32_e32 v146, v200, v146
	s_waitcnt lgkmcnt(0)
	v_mfma_f32_32x32x16_bf16 v[82:97], v[150:153], v[126:129], v[82:97]
	v_add_f32_e32 v146, v201, v146
	v_add_f32_e32 v146, v202, v146
	v_add_f32_e32 v146, v203, v146
	v_add_f32_e32 v146, v204, v146
	v_add_f32_e32 v146, v205, v146
	v_add_f32_e32 v210, v226, v146
	v_mov_b32_e32 v211, v210
	v_cvt_pk_bf16_f32 v146, v206, v207
	v_cvt_pk_bf16_f32 v147, v212, v213
	v_cvt_pk_bf16_f32 v148, v214, v215
	v_cvt_pk_bf16_f32 v149, v216, v217
	v_cvt_pk_bf16_f32 v150, v218, v219
	v_cvt_pk_bf16_f32 v151, v220, v221
	v_cvt_pk_bf16_f32 v152, v222, v223
	v_cvt_pk_bf16_f32 v153, v224, v225
	v_cvt_pk_bf16_f32 v155, v157, v158
	v_cvt_pk_bf16_f32 v156, v159, v160
	v_cvt_pk_bf16_f32 v157, v161, v198
	v_cvt_pk_bf16_f32 v158, v199, v200
	v_cvt_pk_bf16_f32 v159, v201, v202
	v_cvt_pk_bf16_f32 v160, v203, v204
	v_cvt_pk_bf16_f32 v161, v205, v226
	v_permlane32_swap_b32_e32 v210, v211
	v_permlane32_swap_b32_e32 v146, v148
	v_permlane32_swap_b32_e32 v147, v149
	v_permlane32_swap_b32_e32 v150, v152
	v_permlane32_swap_b32_e32 v151, v153
	v_permlane32_swap_b32_e32 v154, v156
	v_permlane32_swap_b32_e32 v155, v157
	v_permlane32_swap_b32_e32 v158, v160
	v_permlane32_swap_b32_e32 v159, v161
	s_andn2_b64 vcc, exec, s[0:1]
	s_cbranch_vccnz .LBB0_266
	s_add_u32 s0, s90, 64
	s_addc_u32 s1, s91, 0
	s_cmpk_lt_u32 s4, 0xfe
	s_cselect_b32 s1, s1, s44
	s_cselect_b32 s0, s0, s31
	s_lshl_b64 s[0:1], s[0:1], 9
	v_lshl_add_u64 v[130:131], v[168:169], 0, s[0:1]
	v_add_co_u32_e32 v134, vcc, 0x4000, v130
	v_lshl_add_u64 v[138:139], v[170:171], 0, s[0:1]
	s_nop 0
	v_addc_co_u32_e32 v135, vcc, 0, v131, vcc
	v_add_co_u32_e32 v142, vcc, 0x4000, v138
	global_load_dwordx4 v[130:133], v[130:131], off
	global_load_dwordx4 v[134:137], v[134:135], off
	v_addc_co_u32_e32 v143, vcc, 0, v139, vcc
	global_load_dwordx4 v[138:141], v[138:139], off
	global_load_dwordx4 v[142:145], v[142:143], off

; #define SBAR() __builtin_amdgcn_sched_barrier(0)
; __device__ __forceinline__ void partialSM(f32x16& p0, f32x16& p1, float& m_reg, float& mn, float& alpha) {
;   constexpr float C = ASCALE * 1.4426950408889634f;
;   float pmax = p0[0];
; #pragma unroll
;   for (int r = 1; r < 16; ++r) pmax = fmaxf(pmax, p0[r]);
; #pragma unroll
;   for (int r = 0; r < 16; ++r) pmax = fmaxf(pmax, p1[r]);
;   { auto rr = __builtin_amdgcn_permlane32_swap(__float_as_uint(pmax), __float_as_uint(pmax), false, false);
;     pmax = fmaxf(__uint_as_float(rr[0]), __uint_as_float(rr[1])); }
;   if (__builtin_expect(__all(pmax - m_reg <= ATHR / ASCALE), 1)) { mn = m_reg; alpha = 1.f; }
;   else { mn = fmaxf(m_reg, pmax); alpha = __builtin_amdgcn_exp2f((m_reg - mn) * C); m_reg = mn; }
; template <int D0> __device__ __forceinline__ void pv_one(f32x16& od, int vb, bf16x8 pa0, bf16x8 pa1, bf16x8 pa2, bf16x8 pa3) {
;   const s16x4 l0 = tr_read<v_rd_off(D0, 0, 0)>(vb), h0 = tr_read<v_rd_off(D0, 0, 1)>(vb), l1 = tr_read<v_rd_off(D0, 1, 0)>(vb), h1 = tr_read<v_rd_off(D0, 1, 1)>(vb);
;   const s16x4 l2 = tr_read<v_rd_off(D0, 2, 0)>(vb), h2 = tr_read<v_rd_off(D0, 2, 1)>(vb), l3 = tr_read<v_rd_off(D0, 3, 0)>(vb), h3 = tr_read<v_rd_off(D0, 3, 1)>(vb);
;   asm volatile("s_waitcnt lgkmcnt(0)" ::: "memory"); SBAR();
;     ...
;   od = __builtin_amdgcn_mfma_f32_32x32x16_bf16(pa0, PK(l0, h0), od, 0, 0, 0);
;   od = __builtin_amdgcn_mfma_f32_32x32x16_bf16(pa1, PK(l1, h1), od, 0, 0, 0);
;   od = __builtin_amdgcn_mfma_f32_32x32x16_bf16(pa2, PK(l2, h2), od, 0, 0, 0);
;   od = __builtin_amdgcn_mfma_f32_32x32x16_bf16(pa3, PK(l3, h3), od, 0, 0, 0);
;     ...
; }
; __device__ __forceinline__ void pv_d0(f32x16* o, int vb, bf16x8 pa0, bf16x8 pa1, bf16x8 pa2, bf16x8 pa3) {
;   pv_one<0>(o[0], vb, pa0, pa1, pa2, pa3); pv_one<1>(o[1], vb, pa0, pa1, pa2, pa3); pv_one<2>(o[2], vb, pa0, pa1, pa2, pa3); pv_one<3>(o[3], vb, pa0, pa1, pa2, pa3);
; }
.Latt_nomask:
	v_add_u32_e32 v198, s9, v178
	ds_read_b64_tr_b16 v[212:213], v198 offset:0
	ds_read_b64_tr_b16 v[214:215], v198 offset:0x800
	ds_read_b64_tr_b16 v[216:217], v198 offset:0x1000
	ds_read_b64_tr_b16 v[218:219], v198 offset:0x1800
	ds_read_b64_tr_b16 v[220:221], v198 offset:0x2000
	ds_read_b64_tr_b16 v[222:223], v198 offset:0x2800
	ds_read_b64_tr_b16 v[224:225], v198 offset:0x3000
	ds_read_b64_tr_b16 v[226:227], v198 offset:0x3800
	s_waitcnt lgkmcnt(6)
	s_nop 0
	v_mfma_f32_32x32x16_bf16 v[2:17], v[146:149], v[212:215], v[2:17]
	ds_read_b64_tr_b16 v[212:213], v198 offset:0x200
	ds_read_b64_tr_b16 v[214:215], v198 offset:0xa00
	s_waitcnt lgkmcnt(6)
	v_mfma_f32_32x32x16_bf16 v[2:17], v[150:153], v[216:219], v[2:17]
	ds_read_b64_tr_b16 v[216:217], v198 offset:0x1200
	ds_read_b64_tr_b16 v[218:219], v198 offset:0x1a00
	s_waitcnt lgkmcnt(6)
	v_mfma_f32_32x32x16_bf16 v[2:17], v[154:157], v[220:223], v[2:17]
	ds_read_b64_tr_b16 v[220:221], v198 offset:0x2200
	ds_read_b64_tr_b16 v[222:223], v198 offset:0x2a00
	s_waitcnt lgkmcnt(6)
	v_mfma_f32_32x32x16_bf16 v[2:17], v[158:161], v[224:227], v[2:17]
	ds_read_b64_tr_b16 v[224:225], v198 offset:0x3200
	ds_read_b64_tr_b16 v[226:227], v198 offset:0x3a00
	s_waitcnt lgkmcnt(6)
	v_mfma_f32_32x32x16_bf16 v[50:65], v[146:149], v[212:215], v[50:65]
	ds_read_b64_tr_b16 v[212:213], v198 offset:0x400
	ds_read_b64_tr_b16 v[214:215], v198 offset:0xc00
	s_waitcnt lgkmcnt(6)
	v_mfma_f32_32x32x16_bf16 v[50:65], v[150:153], v[216:219], v[50:65]
	ds_read_b64_tr_b16 v[216:217], v198 offset:0x1400
	ds_read_b64_tr_b16 v[218:219], v198 offset:0x1c00
	s_waitcnt lgkmcnt(6)
	v_mfma_f32_32x32x16_bf16 v[50:65], v[154:157], v[220:223], v[50:65]
	ds_read_b64_tr_b16 v[220:221], v198 offset:0x2400
	ds_read_b64_tr_b16 v[222:223], v198 offset:0x2c00
	s_waitcnt lgkmcnt(6)
	v_mfma_f32_32x32x16_bf16 v[50:65], v[158:161], v[224:227], v[50:65]
	ds_read_b64_tr_b16 v[224:225], v198 offset:0x3400
	ds_read_b64_tr_b16 v[226:227], v198 offset:0x3c00
	s_waitcnt lgkmcnt(6)
	v_mfma_f32_32x32x16_bf16 v[34:49], v[146:149], v[212:215], v[34:49]
	ds_read_b64_tr_b16 v[212:213], v198 offset:0x600
	ds_read_b64_tr_b16 v[214:215], v198 offset:0xe00
	s_waitcnt lgkmcnt(6)
	v_mfma_f32_32x32x16_bf16 v[34:49], v[150:153], v[216:219], v[34:49]
	ds_read_b64_tr_b16 v[216:217], v198 offset:0x1600
	ds_read_b64_tr_b16 v[218:219], v198 offset:0x1e00
	s_waitcnt lgkmcnt(6)
	v_mfma_f32_32x32x16_bf16 v[34:49], v[154:157], v[220:223], v[34:49]
	ds_read_b64_tr_b16 v[220:221], v198 offset:0x2600
	ds_read_b64_tr_b16 v[222:223], v198 offset:0x2e00
	s_waitcnt lgkmcnt(6)
	v_mfma_f32_32x32x16_bf16 v[34:49], v[158:161], v[224:227], v[34:49]
	ds_read_b64_tr_b16 v[224:225], v198 offset:0x3600
	ds_read_b64_tr_b16 v[226:227], v198 offset:0x3e00
	s_waitcnt lgkmcnt(6)
	v_mfma_f32_32x32x16_bf16 v[18:33], v[146:149], v[212:215], v[18:33]
	v_max_f32_e32 v230, v66, v67
	v_max3_f32 v230, v230, v68, v69
	v_max3_f32 v230, v230, v70, v71
	v_max3_f32 v230, v230, v72, v73
	v_max3_f32 v230, v230, v74, v75
	v_max3_f32 v230, v230, v76, v77
	v_max3_f32 v230, v230, v78, v79
	s_waitcnt lgkmcnt(4)
	v_mfma_f32_32x32x16_bf16 v[18:33], v[150:153], v[216:219], v[18:33]
	v_max3_f32 v230, v230, v80, v81
	v_max3_f32 v230, v230, v82, v83
	v_max3_f32 v230, v230, v84, v85
	v_max3_f32 v230, v230, v86, v87
	v_max3_f32 v230, v230, v88, v89
	v_max3_f32 v230, v230, v90, v91
	v_max3_f32 v230, v230, v92, v93
	v_max3_f32 v230, v230, v94, v95
	s_waitcnt lgkmcnt(2)
	v_mfma_f32_32x32x16_bf16 v[18:33], v[154:157], v[220:223], v[18:33]
	v_max3_f32 v230, v230, v96, v97
	v_mov_b32_e32 v231, v230
	s_nop 1
	v_permlane32_swap_b32_e32 v230, v231
	v_max_f32_e32 v230, v230, v231
	v_sub_f32_e32 v231, v230, v209
	v_cmp_ge_f32_e32 vcc, s25, v231
	v_max_f32_e32 v231, v209, v230
	s_waitcnt lgkmcnt(0)
	v_mfma_f32_32x32x16_bf16 v[18:33], v[158:161], v[224:227], v[18:33]
	v_sub_f32_e32 v230, v209, v231
	v_mul_f32_e32 v230, 0x3e0293ee, v230
	s_cmp_eq_u64 vcc, exec
	v_exp_f32_e32 v230, v230
	s_cselect_b64 s[40:41], -1, 0
	s_add_i32 s0, s8, 0
	v_add_u32_e32 v232, s0, v176
	s_waitcnt vmcnt(0)
	s_waitcnt vmcnt(3)
	ds_write_b128 v232, v[130:133]
	v_cndmask_b32_e64 v230, v230, 1.0, s[40:41]
	s_waitcnt vmcnt(2)
	ds_write_b128 v232, v[134:137] offset:8192
	v_add_u32_e32 v232, s0, v179
	s_waitcnt vmcnt(1)
	ds_write_b128 v232, v[138:141] offset:49152
	v_cmp_gt_f32_e32 vcc, 1.0, v230
	s_waitcnt vmcnt(0)
	ds_write_b128 v232, v[142:145] offset:57344
	s_cbranch_vccz .LBB0_270
	s_and_saveexec_b64 s[0:1], s[38:39]
	ds_write_b32 v190, v230 offset:128
	s_or_b64 exec, exec, s[0:1]
	s_waitcnt lgkmcnt(0)
	v_add_u32_e32 v236, v173, v181
	ds_read_b128 v[232:235], v236 offset:224
	ds_read_b128 v[130:133], v236 offset:192
	ds_read_b128 v[134:137], v236 offset:160
	ds_read_b128 v[138:141], v236 offset:128
	s_waitcnt lgkmcnt(3)
	v_pk_mul_f32 v[14:15], v[14:15], v[232:233]
	s_waitcnt lgkmcnt(2)
	v_pk_mul_f32 v[10:11], v[10:11], v[130:131]
	s_waitcnt lgkmcnt(1)
	v_pk_mul_f32 v[6:7], v[6:7], v[134:135]
	v_pk_mul_f32 v[16:17], v[16:17], v[234:235]
	v_pk_mul_f32 v[12:13], v[12:13], v[132:133]
	v_pk_mul_f32 v[8:9], v[8:9], v[136:137]
	s_waitcnt lgkmcnt(0)
	v_pk_mul_f32 v[4:5], v[4:5], v[140:141]
	v_pk_mul_f32 v[2:3], v[2:3], v[138:139]
	v_pk_mul_f32 v[62:63], v[62:63], v[232:233]
	v_pk_mul_f32 v[58:59], v[58:59], v[130:131]
	v_pk_mul_f32 v[54:55], v[54:55], v[134:135]
	v_pk_mul_f32 v[64:65], v[64:65], v[234:235]
	v_pk_mul_f32 v[60:61], v[60:61], v[132:133]
	v_pk_mul_f32 v[56:57], v[56:57], v[136:137]
	v_pk_mul_f32 v[52:53], v[52:53], v[140:141]
	v_pk_mul_f32 v[50:51], v[50:51], v[138:139]
	v_pk_mul_f32 v[46:47], v[46:47], v[232:233]
	v_pk_mul_f32 v[42:43], v[42:43], v[130:131]
	v_pk_mul_f32 v[38:39], v[38:39], v[134:135]
	v_pk_mul_f32 v[48:49], v[48:49], v[234:235]
	v_pk_mul_f32 v[44:45], v[44:45], v[132:133]
	v_pk_mul_f32 v[40:41], v[40:41], v[136:137]
	v_pk_mul_f32 v[36:37], v[36:37], v[140:141]
	v_pk_mul_f32 v[34:35], v[34:35], v[138:139]
	v_pk_mul_f32 v[30:31], v[30:31], v[232:233]
	v_pk_mul_f32 v[26:27], v[26:27], v[130:131]
	v_pk_mul_f32 v[22:23], v[22:23], v[134:135]
	v_pk_mul_f32 v[32:33], v[32:33], v[234:235]
	v_pk_mul_f32 v[28:29], v[28:29], v[132:133]
	v_pk_mul_f32 v[24:25], v[24:25], v[136:137]
	v_pk_mul_f32 v[20:21], v[20:21], v[140:141]
	v_pk_mul_f32 v[18:19], v[18:19], v[138:139]
